# DA attention loop: s_setprio 1 only around the next-tile K/V global load issue block
# baseline (speedup 1.0000x reference)
.LBB0_279:
	s_setprio 1
	v_mul_u32_u24_e32 v66, s36, v150
	v_mul_u32_u24_e32 v67, s36, v154
	v_mul_u32_u24_e32 v68, s36, v158
	v_mul_u32_u24_e32 v69, s36, v162
	v_add_lshl_u32 v66, v66, v152, 1
	v_add_lshl_u32 v67, v67, v156, 1
	v_add_lshl_u32 v68, v68, v160, 1
	v_add_lshl_u32 v69, v69, v164, 1
	global_load_dwordx4 v[118:121], v66, s[10:11]
	global_load_dwordx4 v[114:117], v67, s[10:11]
	global_load_dwordx4 v[126:129], v68, s[10:11]
	global_load_dwordx4 v[122:125], v69, s[10:11]
	v_mul_u32_u24_e32 v66, s12, v166
	v_mul_u32_u24_e32 v67, s12, v170
	v_mul_u32_u24_e32 v68, s12, v172
	v_mul_u32_u24_e32 v69, s12, v174
	v_lshl_add_u32 v66, v66, 1, v0
	v_lshl_add_u32 v67, v67, 1, v0
	v_lshl_add_u32 v68, v68, 1, v0
	v_lshl_add_u32 v69, v69, 1, v0
	global_load_dwordx4 v[134:137], v66, s[8:9]
	global_load_dwordx4 v[130:133], v67, s[8:9]
	global_load_dwordx4 v[142:145], v68, s[8:9]
	global_load_dwordx4 v[138:141], v69, s[8:9]
	s_setprio 0
	v_add_u32_e32 v0, s79, v213
	v_lshlrev_b32_e32 v78, 1, v205
	v_lshlrev_b32_e32 v79, 1, v148
	v_add3_u32 v0, v0, v78, v79
	ds_read_b128 v[218:221], v0
	ds_read_b128 v[222:225], v0 offset:32
	ds_read_b128 v[226:229], v0 offset:8704
	ds_read_b128 v[230:233], v0 offset:8736
	ds_read_b128 v[234:237], v0 offset:64
	ds_read_b128 v[238:241], v0 offset:96
	ds_read_b128 v[242:245], v0 offset:8768
	ds_read_b128 v[246:249], v0 offset:8800
	v_xor_b32_e32 v66, 0x80000000, v216
	v_mov_b32_e32 v67, v66
	v_mov_b32_e32 v68, v66
	v_mov_b32_e32 v69, v66
	v_mov_b32_e32 v70, v66
	v_mov_b32_e32 v71, v66
	v_mov_b32_e32 v72, v66
	v_mov_b32_e32 v73, v66
	v_mov_b32_e32 v74, v66
	v_mov_b32_e32 v75, v66
	v_mov_b32_e32 v76, v66
	v_mov_b32_e32 v77, v66
	v_mov_b32_e32 v78, v66
	v_mov_b32_e32 v79, v66
	v_mov_b32_e32 v80, v66
	v_mov_b32_e32 v81, v66
	s_waitcnt lgkmcnt(7)
	s_nop 0
	v_mfma_f32_32x32x16_bf16 v[82:97], v[218:221], v[98:101], v[66:81]
	s_mov_b32 s0, 0x41600000
	s_waitcnt lgkmcnt(6)
	v_mfma_f32_32x32x16_bf16 v[82:97], v[222:225], v[102:105], v[82:97]
	s_waitcnt lgkmcnt(5)
	v_mfma_f32_32x32x16_bf16 v[66:81], v[226:229], v[98:101], v[66:81]
	s_waitcnt lgkmcnt(3)
	v_mfma_f32_32x32x16_bf16 v[82:97], v[234:237], v[106:109], v[82:97]
	v_mfma_f32_32x32x16_bf16 v[66:81], v[230:233], v[102:105], v[66:81]
	s_waitcnt lgkmcnt(2)
	v_mfma_f32_32x32x16_bf16 v[82:97], v[238:241], v[110:113], v[82:97]
	s_waitcnt lgkmcnt(1)
	v_mfma_f32_32x32x16_bf16 v[66:81], v[242:245], v[106:109], v[66:81]
	s_nop 9
	v_max_f32_e32 v0, v83, v83
	v_max_f32_e32 v217, v82, v82
	v_max_f32_e32 v0, v217, v0
	v_max3_f32 v0, v0, v84, v85
	v_max3_f32 v0, v0, v86, v87
	v_max3_f32 v0, v0, v88, v89
	v_max3_f32 v0, v0, v90, v91
	s_waitcnt lgkmcnt(0)
	v_mfma_f32_32x32x16_bf16 v[66:81], v[246:249], v[110:113], v[66:81]
	v_max3_f32 v0, v0, v92, v93
	v_max3_f32 v0, v0, v94, v95
	v_max3_f32 v0, v0, v96, v97
	s_nop 8
	v_max3_f32 v0, v0, v66, v67
	v_max3_f32 v0, v0, v68, v69
	v_max3_f32 v0, v0, v70, v71
	v_max3_f32 v0, v0, v72, v73
	v_max3_f32 v0, v0, v74, v75
	v_max3_f32 v0, v0, v76, v77
	v_max3_f32 v0, v0, v78, v79
	v_max3_f32 v0, v0, v80, v81
	v_cmp_lt_f32_e32 vcc, s0, v0
	s_cbranch_vccz .LBB0_270
	v_cmp_lt_i32_e32 vcc, v186, v185
	s_nop 1
	v_cndmask_b32_e32 v217, v183, v186, vcc
	v_lshlrev_b32_e32 v217, 2, v217
	ds_bpermute_b32 v217, v217, v0
	s_waitcnt lgkmcnt(0)
	v_max3_f32 v0, v0, v217, 0
	v_exp_f32_e64 v218, -v0
	v_add_f32_e32 v216, v216, v0
	v_pk_add_f32 v[82:83], v[82:83], v[0:1] op_sel_hi:[1,0] neg_lo:[0,1] neg_hi:[0,1]
	v_pk_add_f32 v[66:67], v[66:67], v[0:1] op_sel_hi:[1,0] neg_lo:[0,1] neg_hi:[0,1]
	v_pk_add_f32 v[84:85], v[84:85], v[0:1] op_sel_hi:[1,0] neg_lo:[0,1] neg_hi:[0,1]
	v_pk_add_f32 v[68:69], v[68:69], v[0:1] op_sel_hi:[1,0] neg_lo:[0,1] neg_hi:[0,1]
	v_pk_add_f32 v[86:87], v[86:87], v[0:1] op_sel_hi:[1,0] neg_lo:[0,1] neg_hi:[0,1]
	v_pk_add_f32 v[70:71], v[70:71], v[0:1] op_sel_hi:[1,0] neg_lo:[0,1] neg_hi:[0,1]
	v_pk_add_f32 v[88:89], v[88:89], v[0:1] op_sel_hi:[1,0] neg_lo:[0,1] neg_hi:[0,1]
	v_pk_add_f32 v[72:73], v[72:73], v[0:1] op_sel_hi:[1,0] neg_lo:[0,1] neg_hi:[0,1]
	v_pk_add_f32 v[90:91], v[90:91], v[0:1] op_sel_hi:[1,0] neg_lo:[0,1] neg_hi:[0,1]
	v_pk_add_f32 v[74:75], v[74:75], v[0:1] op_sel_hi:[1,0] neg_lo:[0,1] neg_hi:[0,1]
	v_pk_add_f32 v[92:93], v[92:93], v[0:1] op_sel_hi:[1,0] neg_lo:[0,1] neg_hi:[0,1]
	v_pk_add_f32 v[76:77], v[76:77], v[0:1] op_sel_hi:[1,0] neg_lo:[0,1] neg_hi:[0,1]
	v_pk_add_f32 v[94:95], v[94:95], v[0:1] op_sel_hi:[1,0] neg_lo:[0,1] neg_hi:[0,1]
	v_pk_add_f32 v[78:79], v[78:79], v[0:1] op_sel_hi:[1,0] neg_lo:[0,1] neg_hi:[0,1]
	v_pk_add_f32 v[96:97], v[96:97], v[0:1] op_sel_hi:[1,0] neg_lo:[0,1] neg_hi:[0,1]
	v_pk_add_f32 v[80:81], v[80:81], v[0:1] op_sel_hi:[1,0] neg_lo:[0,1] neg_hi:[0,1]
	v_pk_mul_f32 v[64:65], v[64:65], v[218:219] op_sel_hi:[1,0]
	v_pk_mul_f32 v[62:63], v[62:63], v[218:219] op_sel_hi:[1,0]
	v_pk_mul_f32 v[60:61], v[60:61], v[218:219] op_sel_hi:[1,0]
	v_pk_mul_f32 v[58:59], v[58:59], v[218:219] op_sel_hi:[1,0]
	v_pk_mul_f32 v[56:57], v[56:57], v[218:219] op_sel_hi:[1,0]
	v_pk_mul_f32 v[54:55], v[54:55], v[218:219] op_sel_hi:[1,0]
	v_pk_mul_f32 v[52:53], v[52:53], v[218:219] op_sel_hi:[1,0]
	v_pk_mul_f32 v[50:51], v[50:51], v[218:219] op_sel_hi:[1,0]
	v_pk_mul_f32 v[48:49], v[48:49], v[218:219] op_sel_hi:[1,0]
	v_pk_mul_f32 v[46:47], v[46:47], v[218:219] op_sel_hi:[1,0]
	v_pk_mul_f32 v[44:45], v[44:45], v[218:219] op_sel_hi:[1,0]
	v_pk_mul_f32 v[42:43], v[42:43], v[218:219] op_sel_hi:[1,0]
	v_pk_mul_f32 v[40:41], v[40:41], v[218:219] op_sel_hi:[1,0]
	v_pk_mul_f32 v[38:39], v[38:39], v[218:219] op_sel_hi:[1,0]
	v_pk_mul_f32 v[36:37], v[36:37], v[218:219] op_sel_hi:[1,0]
	v_pk_mul_f32 v[34:35], v[34:35], v[218:219] op_sel_hi:[1,0]
	v_pk_mul_f32 v[32:33], v[32:33], v[218:219] op_sel_hi:[1,0]
	v_pk_mul_f32 v[30:31], v[30:31], v[218:219] op_sel_hi:[1,0]
	v_pk_mul_f32 v[28:29], v[28:29], v[218:219] op_sel_hi:[1,0]
	v_pk_mul_f32 v[26:27], v[26:27], v[218:219] op_sel_hi:[1,0]
	v_pk_mul_f32 v[24:25], v[24:25], v[218:219] op_sel_hi:[1,0]
	v_pk_mul_f32 v[22:23], v[22:23], v[218:219] op_sel_hi:[1,0]
	v_pk_mul_f32 v[20:21], v[20:21], v[218:219] op_sel_hi:[1,0]
	v_pk_mul_f32 v[18:19], v[18:19], v[218:219] op_sel_hi:[1,0]
	v_pk_mul_f32 v[16:17], v[16:17], v[218:219] op_sel_hi:[1,0]
	v_pk_mul_f32 v[14:15], v[14:15], v[218:219] op_sel_hi:[1,0]
	v_pk_mul_f32 v[12:13], v[12:13], v[218:219] op_sel_hi:[1,0]
	v_pk_mul_f32 v[10:11], v[10:11], v[218:219] op_sel_hi:[1,0]
	v_pk_mul_f32 v[8:9], v[8:9], v[218:219] op_sel_hi:[1,0]
	v_pk_mul_f32 v[6:7], v[6:7], v[218:219] op_sel_hi:[1,0]
	v_pk_mul_f32 v[4:5], v[4:5], v[218:219] op_sel_hi:[1,0]
	v_pk_mul_f32 v[2:3], v[2:3], v[218:219] op_sel_hi:[1,0]
	v_mul_f32_e32 v215, v215, v218
	s_branch .LBB0_270
